# v118 with GEMM9 taking its two M groups in written order (group flip replaced by s_nop, 4x8 rounds kept)
# speedup vs baseline: 1.0080x; 1.0080x over previous
; template <int GI>
; __device__ __forceinline__ bool sched_next(unsigned char* ws, int i, int G, int c, GUnit& u) {
;     ...
;         constexpr int nwg = d.nM * d.nN;
;         if (L >= nwg) return false;
;         int wgid = L;
;         { constexpr int q = nwg / 8, r = nwg % 8; const int xcd = wgid % 8, off = wgid / 8; wgid = (xcd < r ? xcd * (q + 1) : r * (q + 1) + (xcd - r) * q) + off; }
;         constexpr int nig = 8 * d.nN; const int gid = wgid / nig, fm = gid * 8, gsz = (d.nM - fm) < 8 ? (d.nM - fm) : 8;
;         const int pm = fm + ((wgid % nig) % gsz), pn = (wgid % nig) / gsz;
; template <int GI>
; __device__ __forceinline__ void gemm_phase(LAS unsigned char* lds, unsigned char* ws, int G, int cblk) {
;     ...
;     const int tid = tid_, wid = __builtin_amdgcn_readfirstlane(tid >> 6), lane = tid & 63, wr = wid >> 2, wc = wid & 3, fr = lane & 15, fq = lane >> 4;
;     constexpr int K = g.K, nt = K / BK, lda = g.lda, ldb = g.ldb;
;     unsigned voffA[2], voffB[2];
; #pragma unroll
;     for (int i = 0; i < 2; ++i) { int R, C; stage_rc(tid * 16 + i * 8192, R, C); const int Rb = (R & ~31) + perm32(R & 31);
;         voffA[i] = (unsigned)(R * lda + C) * 2u; voffB[i] = (unsigned)(Rb * ldb + C) * 2u; }
;     const size_t kstep = (size_t)(BK * 2);
;     const size_t hstepA = (size_t)HALF * lda * 2, hstepB = (size_t)HALF * ldb * 2;
;     const unsigned ldsw = (unsigned)wid * 1024u;
;     const int aoff = lds_byte(wr * 64 + fr, fq * 8), boff = lds_byte(wc * 32 + fr, fq * 8);
;     ...
;     GUnit cur, nxt; int ui = 0;
;     if (!sched_next<GI>(ws, 0, G, cblk, cur)) return;
;     f32x4 acc[2][2][4][2];
; #pragma unroll
;     for (int a = 0; a < 2; ++a)
; #pragma unroll
;         for (int b = 0; b < 2; ++b)
; #pragma unroll
;             for (int m = 0; m < 4; ++m)
; #pragma unroll
;                 for (int n = 0; n < 2; ++n) acc[a][b][m][n] = (f32x4){0.f, 0.f, 0.f, 0.f};
;     bf16x8 At[4][2], B0[2][2], B1[2][2];
;     const char* cA = cur.A; const char* cB = cur.B;
;     PG8_STAGE(PG8_SB(0, 0), cB, voffB); PG8_STAGE(PG8_SB(0, 1), cB + hstepB, voffB); PG8_STAGE(PG8_SA(0, 0), cA, voffA); PG8_STAGE(PG8_SA(0, 1), cA + hstepA, voffA);
;     if (wr == 1) PG8_BAR;
;     PG8_WAIT_V(2); PG8_BAR;
;     PG8_STAGE(PG8_SB(1, 0), cB + kstep, voffB); PG8_STAGE(PG8_SA(1, 0), cA + kstep, voffA); PG8_STAGE(PG8_SB(1, 1), cB + hstepB + kstep, voffB);
;     PG8_WAIT_V(6); PG8_BAR;
.LBB0_884:
	v_ashrrev_i32_e32 v1, 31, v162
	v_lshrrev_b32_e32 v1, 26, v1
	v_add_u32_e32 v1, v162, v1
	v_ashrrev_i32_e32 v8, 6, v1
	v_bfe_i32 v1, v162, 27, 1
	v_lshlrev_b32_e32 v0, 4, v162
	v_lshrrev_b32_e32 v1, 22, v1
	v_add_u32_e32 v1, v0, v1
	v_and_b32_e32 v1, 0xfffffc00, v1
	v_sub_u32_e32 v1, v0, v1
	v_lshrrev_b32_e32 v2, 4, v1
	v_bitop3_b32 v1, v2, v1, 32 bitop3:0x6c
	v_ashrrev_i32_e32 v3, 31, v1
	v_lshrrev_b32_e32 v3, 26, v3
	v_lshlrev_b32_e32 v2, 3, v8
	v_add_u32_e32 v3, v1, v3
	v_and_b32_e32 v2, -16, v2
	v_ashrrev_i32_e32 v9, 6, v3
	v_and_b32_e32 v3, 0xc0, v3
	v_add_u32_e32 v2, v9, v2
	v_lshlrev_b32_e32 v4, 5, v8
	v_sub_u32_e32 v1, v1, v3
	v_mov_b32_e32 v3, 1
	v_and_b32_e32 v10, 32, v4
	v_ashrrev_i16_sdwa v1, v3, sext(v1) dst_sel:DWORD dst_unused:UNUSED_PAD src0_sel:DWORD src1_sel:BYTE_0
	v_lshlrev_b32_e32 v4, 1, v2
	v_lshrrev_b32_e32 v5, 2, v2
	v_and_b32_e32 v6, 3, v9
	s_mov_b32 s0, 0x7fffe0
	v_bfe_i32 v11, v1, 0, 16
	v_and_b32_e32 v4, 24, v4
	v_and_b32_e32 v5, 4, v5
	v_and_or_b32 v6, v2, s0, v6
	s_movk_i32 s6, 0x1600
	v_add_u32_e32 v1, v10, v11
	v_or3_b32 v4, v6, v5, v4
	v_mul_lo_u32 v2, v2, s6
	v_add_lshl_u32 v130, v1, v2, 1
	v_mul_u32_u24_e32 v2, 0x1600, v4
	v_add_u32_e32 v0, 0x2000, v0
	v_add_lshl_u32 v132, v2, v1, 1
	v_ashrrev_i32_e32 v1, 31, v0
	s_add_i32 s1, s1, s3
	s_nop 0
	s_and_b32 s3, s1, 3
	s_bfe_u32 s7, s1, 0x10005
	s_lshl_b32 s7, s7, 2
	s_or_b32 s3, s3, s7
	s_bfe_u32 s7, s1, 0x30002
	s_lshl_b32 s7, s7, 3
	s_or_b32 s3, s3, s7
	s_andn2_b32 s1, s1, 63
	s_or_b32 s1, s1, s3
	v_lshrrev_b32_e32 v1, 22, v1
	s_ashr_i32 s3, s1, 31
	v_add_u32_e32 v1, v0, v1
	s_lshr_b32 s3, s3, 26
	v_ashrrev_i32_e32 v12, 10, v1
	s_add_i32 s3, s1, s3
	v_mul_i32_i24_e32 v1, 0x400, v12
	s_ashr_i32 s7, s3, 6
	s_and_b32 s3, s3, 0xffc0
	v_sub_u32_e32 v0, v0, v1
	s_sub_i32 s1, s1, s3
	v_lshrrev_b32_e32 v1, 4, v0
	s_bfe_i32 s3, s1, 0x80000
	v_bitop3_b32 v0, v1, v0, 32 bitop3:0x6c
	s_bfe_u32 s3, s3, 0x3000c
	v_ashrrev_i32_e32 v2, 31, v0
	s_add_i32 s3, s1, s3
	v_lshrrev_b32_e32 v2, 26, v2
	s_bfe_i32 s8, s3, 0x80000
	s_and_b32 s3, s3, 0xf8
	v_lshlrev_b32_e32 v1, 3, v12
	v_add_u32_e32 v2, v0, v2
	s_sub_i32 s1, s1, s3
	v_and_b32_e32 v1, -16, v1
	v_ashrrev_i32_e32 v13, 6, v2
	v_lshlrev_b32_e32 v4, 5, v12
	s_lshl_b32 s7, s7, 3
	s_sext_i32_i8 s1, s1
	s_ashr_i32 s15, s14, 6
	v_add_u32_e32 v1, v13, v1
	v_and_b32_e32 v14, 32, v4
	v_and_b32_e32 v4, 3, v13
	s_sext_i32_i16 s9, s8
	s_add_i32 s10, s7, s1
	v_and_or_b32 v4, v1, s0, v4
	s_ashr_i32 s18, s14, 8
	s_lshl_b32 s0, s15, 10
	s_lshr_b32 s8, s9, 3
	s_ashr_i32 s11, s10, 31
	s_mul_i32 s3, s10, 0x2c0000
	s_mul_hi_i32 s1, s10, 0x2c0000
	s_add_u32 s38, s35, s3
	s_addc_u32 s39, s46, s1
	s_add_u32 s1, s28, 0x6e00000
	v_and_b32_e32 v2, 0xc0, v2
	s_addc_u32 s3, s29, 0
	s_ashr_i32 s7, s9, 3
	v_sub_u32_e32 v0, v0, v2
	s_bfe_i64 s[12:13], s[8:9], 0x100000
	s_mul_hi_i32 s8, s7, 0x2c0000
	s_mul_i32 s7, s7, 0x2c0000
	v_ashrrev_i16_sdwa v0, v3, sext(v0) dst_sel:DWORD dst_unused:UNUSED_PAD src0_sel:DWORD src1_sel:BYTE_0
	v_lshlrev_b32_e32 v2, 1, v1
	v_lshrrev_b32_e32 v3, 2, v1
	s_add_u32 s40, s1, s7
	v_bfe_i32 v15, v0, 0, 16
	v_and_b32_e32 v2, 24, v2
	v_and_b32_e32 v3, 4, v3
	s_addc_u32 s41, s3, s8
	s_add_i32 s24, s0, 0
	v_add_u32_e32 v0, v14, v15
	v_or3_b32 v2, v4, v3, v2
	v_mul_lo_u32 v1, v1, s6
	s_add_i32 m0, s24, 0x10000
	v_add_lshl_u32 v134, v0, v1, 1
	v_mul_u32_u24_e32 v1, 0x1600, v2
	global_load_lds_dwordx4 v132, s[40:41]
	s_add_i32 m0, s24, 0x12000
	v_add_lshl_u32 v136, v1, v0, 1
	s_add_u32 s8, s40, 0x160000
	global_load_lds_dwordx4 v136, s[40:41]
	s_addc_u32 s9, s41, 0
	s_add_i32 m0, s24, 0x14000
	s_add_i32 s25, s24, 0x2000
	global_load_lds_dwordx4 v132, s[8:9]
	s_add_i32 m0, s24, 0x16000
	v_mov_b32_e32 v139, 0
	global_load_lds_dwordx4 v136, s[8:9]
	s_mov_b32 m0, s24
	s_add_u32 s8, s38, 0x160000
	global_load_lds_dwordx4 v130, s[38:39]
	s_mov_b32 m0, s25
	s_addc_u32 s9, s39, 0
	s_add_i32 s26, s24, 0x4000
	global_load_lds_dwordx4 v134, s[38:39]
	s_mov_b32 m0, s26
	s_add_i32 s27, s24, 0x6000
	global_load_lds_dwordx4 v130, s[8:9]
	s_mov_b32 m0, s27
	v_mov_b32_e32 v133, v139
	global_load_lds_dwordx4 v134, s[8:9]
	v_mov_b32_e32 v137, v139
	v_mov_b32_e32 v131, v139
	v_mov_b32_e32 v135, v139
	s_cmp_eq_u32 s18, 1
	s_mov_b32 s7, 0
	v_lshl_add_u64 v[6:7], s[40:41], 0, v[132:133]
	v_lshl_add_u64 v[2:3], s[40:41], 0, v[136:137]
	s_mov_b32 s19, 0x16000
	v_lshl_add_u64 v[0:1], s[38:39], 0, v[130:131]
	s_cselect_b64 s[8:9], -1, 0
	s_cmp_lg_u32 s18, 1
	v_lshl_add_u64 v[4:5], s[38:39], 0, v[134:135]
	s_cbranch_scc1 .LBB0_886
	s_barrier

; template <int GI>
; __device__ __forceinline__ bool sched_next(unsigned char* ws, int i, int G, int c, GUnit& u) {
;     ...
;         constexpr int nwg = d.nM * d.nN;
;         if (L >= nwg) return false;
;         int wgid = L;
;         { constexpr int q = nwg / 8, r = nwg % 8; const int xcd = wgid % 8, off = wgid / 8; wgid = (xcd < r ? xcd * (q + 1) : r * (q + 1) + (xcd - r) * q) + off; }
;         constexpr int nig = 8 * d.nN; const int gid = wgid / nig, fm = gid * 8, gsz = (d.nM - fm) < 8 ? (d.nM - fm) : 8;
;         const int pm = fm + ((wgid % nig) % gsz), pn = (wgid % nig) / gsz;
;         u.A = (const char*)ws + d.A + (size_t)pm * d.a_tile;
;         u.B = (const char*)ws + d.B + (size_t)(pm >> 4) * d.b_batch + (size_t)pn * d.b_tile;
;         u.C = (char*)ws + d.C + (size_t)pm * d.c_rt + (size_t)pn * d.c_ct;
; template <int GI>
; __device__ __forceinline__ void gemm_phase(LAS unsigned char* lds, unsigned char* ws, int G, int cblk) {
;     ...
;         const bool has_next = sched_next<GI>(ws, ui + 1, G, cblk, nxt);
;         const char* nA = has_next ? nxt.A : cA; const char* nB = has_next ? nxt.B : cB;
.LBB0_894:
	s_ashr_i32 s15, s15, 3
	s_add_i32 s15, s23, s15
	s_nop 0
	s_and_b32 s20, s15, 3
	s_bfe_u32 s21, s15, 0x10005
	s_lshl_b32 s21, s21, 2
	s_or_b32 s20, s20, s21
	s_bfe_u32 s21, s15, 0x30002
	s_lshl_b32 s21, s21, 3
	s_or_b32 s20, s20, s21
	s_andn2_b32 s15, s15, 63
	s_or_b32 s15, s15, s20
	s_ashr_i32 s20, s15, 31
	s_lshr_b32 s20, s20, 26
	s_add_i32 s20, s15, s20
	s_ashr_i32 s21, s20, 6
	s_and_b32 s20, s20, 0xffc0
	s_sub_i32 s15, s15, s20
	s_bfe_i32 s20, s15, 0x80000
	s_bfe_u32 s20, s20, 0x3000c
	s_add_i32 s20, s15, s20
	s_bfe_i32 s22, s20, 0x80000
	s_and_b32 s20, s20, 0xf8
	s_sub_i32 s15, s15, s20
	s_lshl_b32 s21, s21, 3
	s_sext_i32_i8 s15, s15
	s_sext_i32_i16 s23, s22
	s_add_i32 s36, s21, s15
	s_lshr_b32 s22, s23, 3
	s_ashr_i32 s37, s36, 31
	s_mul_i32 s20, s36, 0x2c0000
	s_mul_hi_i32 s15, s36, 0x2c0000
	s_add_u32 s20, s35, s20
	s_addc_u32 s21, s46, s15
	s_ashr_i32 s15, s23, 3
	s_bfe_i64 s[42:43], s[22:23], 0x100000
	s_mul_hi_i32 s23, s15, 0x2c0000
	s_mul_i32 s15, s15, 0x2c0000
	s_add_u32 s22, s1, s15
	s_addc_u32 s23, s3, s23
	s_lshl_b64 s[36:37], s[36:37], 20
	s_add_u32 s15, s33, s36
	s_addc_u32 s34, s47, s37
	s_lshl_b64 s[36:37], s[42:43], 9
	s_add_u32 s36, s15, s36
	s_addc_u32 s37, s34, s37
